# v38: hoist the 6 late K-half loads of the sample-attention QK into the initial load group (counted vmcnt ladder)
# baseline (speedup 1.0000x reference)
; #define LAS __attribute__((address_space(3)))
; template <bool LDSRC>
; __device__ __forceinline__ void attn_core(const Params& p, const int lane, const char* kptr, const int kstride, const char* vptr, const int vstride,
;                                           const int kt0, const int has_prev, const int row_q, const int h_q, const int i_q) {
;     ...
;   f32x4 sa[9];
; #pragma unroll
;   for (int kt = 0; kt < 9; ++kt) {
;     int T = kt0 + kt; if (!has_prev && T < 8) T = 8;
;     const char* kp = kptr + (T * 16 + pl) * kstride + q4 * 16;
;     bf16x8 k0, k1;
;     if constexpr (LDSRC) { k0 = *(const LAS bf16x8*)(const LAS char*)kp; k1 = *(const LAS bf16x8*)(const LAS char*)(kp + 64); }
;     else { k0 = *(const bf16x8*)kp; k1 = *(const bf16x8*)(kp + 64); }
;     f32x4 a = f32x4{0.f, 0.f, 0.f, 0.f};
;     a = __builtin_amdgcn_mfma_f32_16x16x32_bf16(k0, qf0, a, 0, 0, 0);
;     a = __builtin_amdgcn_mfma_f32_16x16x32_bf16(k1, qf1, a, 0, 0, 0);
;     sa[kt] = a;
;   }
;   const int lo = has_prev ? (i_q + 1) : ((i_q + 1) > 128 ? (i_q + 1) : 128);
;   const unsigned span = (unsigned)(i_q + 128 - lo);
;   const int dbase = q4 * 4 - lo;
;   float mx = -INFINITY;
; #pragma unroll
;   for (int kt = 0; kt < 9; ++kt) {
; #pragma unroll
;     for (int r = 0; r < 4; ++r) {
;       const int d = (kt0 + kt) * 16 + r + dbase;
;       const float v = ((unsigned)d <= span) ? sa[kt][r] : -INFINITY;
;       sa[kt][r] = v; mx = fmaxf(mx, v);
;     }
;   }
;   mx = fmaxf(mx, __shfl_xor(mx, 16)); mx = fmaxf(mx, __shfl_xor(mx, 32));
.LBB0_545:
	s_and_saveexec_b64 s[34:35], s[20:21]
	s_cbranch_execz .LBB0_544
	v_readlane_b32 s50, v244, 55
	v_ashrrev_i32_e32 v3, 3, v29
	v_readlane_b32 s51, v244, 56
	v_and_b32_e32 v15, 1, v3
	v_ashrrev_i32_e32 v30, 4, v29
	v_mov_b64_e32 v[16:17], s[50:51]
	v_mad_i64_i32 v[16:17], s[50:51], v30, s37, v[16:17]
	v_lshlrev_b32_e32 v8, 7, v15
	v_lshl_add_u64 v[18:19], v[16:17], 0, v[8:9]
	v_lshl_add_u64 v[18:19], v[18:19], 0, v[82:83]
	v_lshl_add_u64 v[18:19], v[18:19], 0, v[12:13]
	v_add_co_u32_e32 v92, vcc, s41, v18
	v_readlane_b32 s52, v244, 0
	s_nop 0
	v_addc_co_u32_e32 v93, vcc, 0, v19, vcc
	v_add_co_u32_e32 v70, vcc, s36, v18
	v_readlane_b32 s54, v244, 2
	v_readlane_b32 s55, v244, 3
	v_addc_co_u32_e32 v71, vcc, 0, v19, vcc
	v_lshl_add_u32 v16, v30, 2, v21
	v_lshl_or_b32 v17, v15, 2, v20
	v_mov_b64_e32 v[30:31], s[54:55]
	v_add_co_u32_e32 v94, vcc, s44, v18
	v_mad_i64_i32 v[34:35], s[50:51], v16, s38, v[30:31]
	v_lshlrev_b32_e32 v8, 7, v17
	v_addc_co_u32_e32 v95, vcc, 0, v19, vcc
	v_lshl_add_u64 v[34:35], v[34:35], 0, v[8:9]
	v_mov_b32_e32 v15, v9
	v_add_co_u32_e32 v88, vcc, s46, v18
	v_lshl_add_u64 v[42:43], v[34:35], 0, v[14:15]
	s_nop 0
	v_addc_co_u32_e32 v89, vcc, 0, v19, vcc
	global_load_dwordx4 v[30:33], v[18:19], off
	global_load_dwordx4 v[34:37], v[42:43], off offset:1024
	global_load_dwordx4 v[38:41], v[92:93], off offset:-4096
	s_nop 0
	global_load_dwordx4 v[42:45], v[42:43], off offset:1088
	s_nop 0
	global_load_dwordx4 v[46:49], v[18:19], off offset:64
	global_load_dwordx4 v[50:53], v[92:93], off
	global_load_dwordx4 v[54:57], v[70:71], off offset:-4096
	global_load_dwordx4 v[58:61], v[70:71], off
	global_load_dwordx4 v[62:65], v[94:95], off offset:-4096
	global_load_dwordx4 v[66:69], v[94:95], off
	global_load_dwordx4 v[140:143], v[92:93], off offset:-4032
	global_load_dwordx4 v[144:147], v[92:93], off offset:64
	global_load_dwordx4 v[148:151], v[70:71], off offset:-4032
	global_load_dwordx4 v[152:155], v[94:95], off offset:-4032
	global_load_dwordx4 v[156:159], v[94:95], off offset:64
	global_load_dwordx4 v[160:163], v[88:89], off offset:-4032
	s_nop 0
	global_load_dwordx4 v[70:73], v[70:71], off offset:64
	v_add_co_u32_e32 v96, vcc, s40, v18
	global_load_dwordx4 v[74:77], v[88:89], off offset:-4096
	global_load_dwordx4 v[84:87], v[88:89], off
	v_addc_co_u32_e32 v97, vcc, 0, v19, vcc
	global_load_dwordx4 v[88:91], v[88:89], off offset:64
	v_readlane_b32 s68, v244, 35
	v_lshlrev_b32_e32 v15, 2, v17
	v_readlane_b32 s70, v244, 37
	v_readlane_b32 s71, v244, 38
	v_readlane_b32 s53, v244, 1
	v_readlane_b32 s69, v244, 36
	v_readlane_b32 s72, v244, 39
	v_readlane_b32 s73, v244, 40
	v_readlane_b32 s74, v244, 41
	global_load_dword v15, v15, s[70:71]
	v_readlane_b32 s75, v244, 42
	v_readlane_b32 s76, v244, 43
	v_readlane_b32 s77, v244, 44
	v_readlane_b32 s78, v244, 45
	v_readlane_b32 s79, v244, 46
	v_readlane_b32 s80, v244, 47
	v_readlane_b32 s81, v244, 48
	v_readlane_b32 s82, v244, 49
	v_readlane_b32 s83, v244, 50
	s_waitcnt vmcnt(18)
	v_mfma_f32_16x16x32_bf16 v[38:41], v[38:41], v[34:37], 0
	v_mfma_f32_16x16x32_bf16 v[30:33], v[30:33], v[34:37], 0
	s_waitcnt vmcnt(15)
	v_mfma_f32_16x16x32_bf16 v[50:53], v[50:53], v[34:37], 0
	s_waitcnt vmcnt(14)
	v_mfma_f32_16x16x32_bf16 v[54:57], v[54:57], v[34:37], 0
	s_waitcnt vmcnt(13)
	v_mfma_f32_16x16x32_bf16 v[58:61], v[58:61], v[34:37], 0
	s_waitcnt vmcnt(12)
	v_mfma_f32_16x16x32_bf16 v[62:65], v[62:65], v[34:37], 0
	s_waitcnt vmcnt(11)
	v_mfma_f32_16x16x32_bf16 v[66:69], v[66:69], v[34:37], 0
	s_waitcnt vmcnt(3)
	v_mfma_f32_16x16x32_bf16 v[74:77], v[74:77], v[34:37], 0
	s_waitcnt vmcnt(2)
	v_mfma_f32_16x16x32_bf16 v[34:37], v[84:87], v[34:37], 0
	s_nop 0
	v_mfma_f32_16x16x32_bf16 v[30:33], v[46:49], v[42:45], v[30:33]
	s_nop 0
	s_nop 1
	s_nop 0
	s_nop 0
	v_mfma_f32_16x16x32_bf16 v[58:61], v[70:73], v[42:45], v[58:61]
	s_nop 1
	v_cndmask_b32_e64 v17, v22, v30, s[4:5]
	s_waitcnt vmcnt(1)
	v_mfma_f32_16x16x32_bf16 v[38:41], v[140:143], v[42:45], v[38:41]
	s_nop 0
	s_waitcnt vmcnt(0)
	v_mfma_f32_16x16x32_bf16 v[50:53], v[144:147], v[42:45], v[50:53]
	s_nop 0
	s_nop 1
	s_nop 0
	s_nop 0
	s_nop 1
	s_nop 0
	s_nop 0
	v_mfma_f32_16x16x32_bf16 v[46:49], v[148:151], v[42:45], v[54:57]
	v_cmp_lt_i32_e32 vcc, v26, v27
	s_nop 1
	s_nop 0
	v_mfma_f32_16x16x32_bf16 v[34:37], v[88:91], v[42:45], v[34:37]
	v_cndmask_b32_e32 v19, v23, v26, vcc
	v_lshlrev_b32_e32 v110, 2, v19
	v_cmp_lt_i32_e32 vcc, v28, v27
	s_waitcnt vmcnt(0)
	v_mfma_f32_16x16x32_bf16 v[54:57], v[152:155], v[42:45], v[62:65]
	s_nop 2
	s_nop 0
	v_cndmask_b32_e64 v81, v22, v34, s[12:13]
	v_cndmask_b32_e64 v107, v22, v35, s[14:15]
	v_cndmask_b32_e64 v108, v22, v36, s[16:17]
	v_cndmask_b32_e64 v109, v22, v37, s[18:19]
	s_waitcnt vmcnt(0)
	v_mfma_f32_16x16x32_bf16 v[62:65], v[156:159], v[42:45], v[66:69]
	v_mfma_f32_16x16x32_bf16 v[66:69], v[160:163], v[42:45], v[74:77]
	v_cndmask_b32_e64 v45, v22, v31, s[6:7]
	v_cndmask_b32_e64 v72, v22, v32, s[8:9]
	v_cndmask_b32_e64 v73, v33, v22, s[10:11]
	v_max3_f32 v18, v17, s47, v45
	v_max3_f32 v18, v18, v72, v73
	v_max3_f32 v18, v18, v38, v39
	v_max3_f32 v18, v18, v40, v41
	v_max3_f32 v18, v18, v50, v51
	v_max3_f32 v18, v18, v52, v53
	v_max3_f32 v18, v18, v46, v47
	v_max3_f32 v18, v18, v48, v49
	v_max3_f32 v18, v18, v58, v59
	v_max3_f32 v18, v18, v60, v61
	v_max3_f32 v18, v18, v54, v55
	v_max3_f32 v18, v18, v56, v57
	v_max3_f32 v18, v18, v62, v63
	v_max3_f32 v18, v18, v64, v65
	v_max3_f32 v18, v18, v66, v67
	v_max3_f32 v18, v18, v68, v69
	v_max3_f32 v18, v18, v81, v107
	v_max3_f32 v18, v18, v108, v109
	ds_bpermute_b32 v19, v110, v18
	v_mad_i64_i32 v[42:43], s[50:51], v3, s39, v[4:5]
	v_lshl_add_u64 v[70:71], v[42:43], 0, v[6:7]
	global_load_dwordx2 v[30:31], v[70:71], off
	global_load_dwordx2 v[32:33], v[70:71], off offset:32
	s_waitcnt lgkmcnt(0)
; __device__ __forceinline__ unsigned pk2(float lo, float hi) { f32x2 v = {lo, hi}; bf16v2_t b = __builtin_convertvector(v, bf16v2_t); return __builtin_bit_cast(unsigned, b); }
; template <bool LDSRC>
; __device__ __forceinline__ void attn_core(const Params& p, const int lane, const char* kptr, const int kstride, const char* vptr, const int vstride,
;                                           const int kt0, const int has_prev, const int row_q, const int h_q, const int i_q) {
;     ...
;   mx = fmaxf(mx, __shfl_xor(mx, 16)); mx = fmaxf(mx, __shfl_xor(mx, 32));
;   const float mfin = fmaxf(mx * 0.125f, sink);
;   const float cl = 0.125f * 1.4426950408889634f, ml = mfin * 1.4426950408889634f;
;   float sum = 0.f;
; #pragma unroll
;   for (int kt = 0; kt < 9; ++kt) {
; #pragma unroll
;     for (int r = 0; r < 4; ++r) { const float e = __builtin_amdgcn_exp2f(fmaf(sa[kt][r], cl, -ml)); sa[kt][r] = e; sum += e; }
;   }
;   sum += __shfl_xor(sum, 16); sum += __shfl_xor(sum, 32);
;   const float inv = 1.f / (sum + __builtin_amdgcn_exp2f((sink - mfin) * 1.4426950408889634f));
;   f32x4 oa[4];
; #pragma unroll
;   for (int dt = 0; dt < 4; ++dt) oa[dt] = f32x4{0.f, 0.f, 0.f, 0.f};
; #pragma unroll
;   for (int pp = 0; pp < 5; ++pp) {
;     const int kA = 2 * pp, kB = (2 * pp + 1 < 9) ? 2 * pp + 1 : 2 * pp;
;     u32x4 pw;
;     pw.x = pk2(sa[kA][0] * inv, sa[kA][1] * inv); pw.y = pk2(sa[kA][2] * inv, sa[kA][3] * inv);
;     if (2 * pp + 1 < 9) { pw.z = pk2(sa[kB][0] * inv, sa[kB][1] * inv); pw.w = pk2(sa[kB][2] * inv, sa[kB][3] * inv); }
;     else { pw.z = 0u; pw.w = 0u; }
;     const bf16x8 pf = __builtin_bit_cast(bf16x8, pw);
	v_max_f32_e32 v3, v19, v19
	v_max_f32_e32 v3, v18, v3
	v_cndmask_b32_e32 v18, v23, v28, vcc
	v_lshlrev_b32_e32 v112, 2, v18
	ds_bpermute_b32 v44, v112, v3
	v_add_co_u32_e32 v18, vcc, s40, v70
	s_waitcnt lgkmcnt(0)
	v_max_f32_e32 v44, v44, v44
	v_max_f32_e32 v3, v3, v44
	v_mul_f32_e32 v3, 0x3e000000, v3
	v_max_f32_e32 v44, v15, v15
	v_max_f32_e32 v3, v3, v44
	v_mul_f32_e32 v111, 0xbfb8aa3b, v3
	v_fmamk_f32 v17, v17, 0x3e38aa3b, v111
	v_exp_f32_e32 v44, v17
	v_fmamk_f32 v17, v45, 0x3e38aa3b, v111
	v_exp_f32_e32 v45, v17
	v_fmamk_f32 v17, v72, 0x3e38aa3b, v111
	v_exp_f32_e32 v72, v17
	v_fmamk_f32 v17, v73, 0x3e38aa3b, v111
	v_exp_f32_e32 v73, v17
	v_fmamk_f32 v17, v38, 0x3e38aa3b, v111
	v_exp_f32_e32 v74, v17
	v_fmamk_f32 v17, v39, 0x3e38aa3b, v111
	v_exp_f32_e32 v75, v17
	v_fmamk_f32 v17, v40, 0x3e38aa3b, v111
	v_exp_f32_e32 v76, v17
	v_fmamk_f32 v17, v41, 0x3e38aa3b, v111
	v_exp_f32_e32 v77, v17
	v_fmamk_f32 v17, v50, 0x3e38aa3b, v111
	v_exp_f32_e32 v84, v17
	v_fmamk_f32 v17, v51, 0x3e38aa3b, v111
	v_exp_f32_e32 v85, v17
	v_fmamk_f32 v17, v52, 0x3e38aa3b, v111
	v_exp_f32_e32 v86, v17
	v_fmamk_f32 v17, v53, 0x3e38aa3b, v111
	v_exp_f32_e32 v87, v17
	v_fmamk_f32 v17, v46, 0x3e38aa3b, v111
	v_exp_f32_e32 v88, v17
	v_fmamk_f32 v17, v47, 0x3e38aa3b, v111
	v_exp_f32_e32 v89, v17
	v_fmamk_f32 v17, v48, 0x3e38aa3b, v111
	v_exp_f32_e32 v90, v17
	v_fmamk_f32 v17, v49, 0x3e38aa3b, v111
	v_exp_f32_e32 v91, v17
	v_fmamk_f32 v17, v58, 0x3e38aa3b, v111
	v_exp_f32_e32 v92, v17
	v_fmamk_f32 v17, v59, 0x3e38aa3b, v111
	v_exp_f32_e32 v93, v17
	v_fmamk_f32 v17, v60, 0x3e38aa3b, v111
	v_exp_f32_e32 v60, v17
	v_fmamk_f32 v17, v61, 0x3e38aa3b, v111
	v_exp_f32_e32 v61, v17
	v_fmamk_f32 v17, v54, 0x3e38aa3b, v111
	v_exp_f32_e32 v94, v17
	v_fmamk_f32 v17, v55, 0x3e38aa3b, v111
	v_exp_f32_e32 v95, v17
	v_fmamk_f32 v17, v56, 0x3e38aa3b, v111
	v_exp_f32_e32 v96, v17
	v_fmamk_f32 v17, v57, 0x3e38aa3b, v111
	v_exp_f32_e32 v97, v17
	v_fmamk_f32 v17, v62, 0x3e38aa3b, v111
	v_exp_f32_e32 v98, v17
	v_fmamk_f32 v17, v63, 0x3e38aa3b, v111
	v_exp_f32_e32 v99, v17
	v_fmamk_f32 v17, v64, 0x3e38aa3b, v111
	v_exp_f32_e32 v100, v17
	v_fmamk_f32 v17, v65, 0x3e38aa3b, v111
	v_exp_f32_e32 v101, v17
	v_fmamk_f32 v17, v66, 0x3e38aa3b, v111
	v_exp_f32_e32 v102, v17
	v_fmamk_f32 v17, v67, 0x3e38aa3b, v111
	v_exp_f32_e32 v103, v17
	v_fmamk_f32 v17, v68, 0x3e38aa3b, v111
	v_exp_f32_e32 v104, v17
	v_fmamk_f32 v17, v69, 0x3e38aa3b, v111
	v_exp_f32_e32 v105, v17
	v_fmamk_f32 v17, v81, 0x3e38aa3b, v111
	v_exp_f32_e32 v106, v17
	v_fmamk_f32 v17, v107, 0x3e38aa3b, v111
	v_exp_f32_e32 v107, v17
	v_fmamk_f32 v17, v108, 0x3e38aa3b, v111
	v_exp_f32_e32 v108, v17
	v_add_f32_e32 v17, 0, v44
	v_add_f32_e32 v17, v45, v17
	v_add_f32_e32 v17, v72, v17
	v_add_f32_e32 v17, v73, v17
	v_add_f32_e32 v17, v74, v17
	v_add_f32_e32 v17, v75, v17
	v_add_f32_e32 v17, v76, v17
	v_add_f32_e32 v17, v77, v17
	v_add_f32_e32 v17, v84, v17
	v_add_f32_e32 v17, v85, v17
	v_add_f32_e32 v17, v86, v17
	v_add_f32_e32 v17, v87, v17
	v_add_f32_e32 v17, v88, v17
	v_add_f32_e32 v17, v89, v17
	v_add_f32_e32 v17, v90, v17
	v_add_f32_e32 v17, v91, v17
	v_add_f32_e32 v17, v92, v17
	v_add_f32_e32 v17, v93, v17
	v_add_f32_e32 v17, v60, v17
	v_add_f32_e32 v17, v61, v17
	v_add_f32_e32 v17, v94, v17
	v_add_f32_e32 v17, v95, v17
	v_add_f32_e32 v17, v96, v17
	v_add_f32_e32 v17, v97, v17
	v_add_f32_e32 v17, v98, v17
	v_add_f32_e32 v17, v99, v17
	v_add_f32_e32 v17, v100, v17
	v_add_f32_e32 v17, v101, v17
	v_add_f32_e32 v17, v102, v17
	v_add_f32_e32 v17, v103, v17
	v_fmac_f32_e32 v111, 0x3e38aa3b, v109
	v_add_f32_e32 v17, v104, v17
	v_exp_f32_e32 v109, v111
	v_add_f32_e32 v17, v105, v17
	v_add_f32_e32 v17, v106, v17
	v_add_f32_e32 v17, v107, v17
	v_add_f32_e32 v17, v108, v17
	v_add_f32_e32 v17, v109, v17
	ds_bpermute_b32 v38, v110, v17
	v_sub_f32_e32 v3, v15, v3
	v_mul_f32_e32 v3, 0x3fb8aa3b, v3
	v_exp_f32_e32 v3, v3
	v_addc_co_u32_e32 v19, vcc, 0, v71, vcc
	s_waitcnt lgkmcnt(0)
	v_add_f32_e32 v15, v17, v38
	ds_bpermute_b32 v17, v112, v15
	v_add_co_u32_e32 v110, vcc, s41, v70
	global_load_dwordx2 v[34:35], v[18:19], off offset:512
	global_load_dwordx2 v[36:37], v[18:19], off offset:544
	v_addc_co_u32_e32 v111, vcc, 0, v71, vcc
	s_waitcnt lgkmcnt(0)
	v_add_f32_e32 v15, v15, v17
	v_add_f32_e32 v3, v3, v15
	v_div_scale_f32 v15, s[50:51], v3, v3, 1.0
	v_rcp_f32_e32 v17, v15
	global_load_dwordx2 v[38:39], v[110:111], off offset:1024
	global_load_dwordx2 v[40:41], v[110:111], off offset:1056
	v_lshl_add_u64 v[112:113], v[42:43], 0, v[10:11]
	global_load_dwordx2 v[42:43], v[112:113], off
	global_load_dwordx2 v[46:47], v[70:71], off offset:64
	global_load_dwordx2 v[48:49], v[70:71], off offset:96
	v_fma_f32 v50, -v15, v17, 1.0
	v_fmac_f32_e32 v17, v50, v17
	v_div_scale_f32 v50, vcc, 1.0, v3, 1.0
	v_mul_f32_e32 v51, v50, v17
	v_fma_f32 v52, -v15, v51, v50
	v_fmac_f32_e32 v51, v52, v17
	v_fma_f32 v15, -v15, v51, v50
	v_div_fmas_f32 v15, v15, v17, v51
	v_div_fixup_f32 v114, v15, v3, 1.0
	v_pk_mul_f32 v[44:45], v[44:45], v[114:115] op_sel_hi:[1,0]
	v_ashrrev_i32_e32 v17, 31, v16
	v_cvt_pk_bf16_f32 v50, v44, v45
	v_pk_mul_f32 v[44:45], v[72:73], v[114:115] op_sel_hi:[1,0]
	v_lshlrev_b64 v[16:17], 10, v[16:17]
	v_cvt_pk_bf16_f32 v51, v44, v45
	v_pk_mul_f32 v[44:45], v[74:75], v[114:115] op_sel_hi:[1,0]
	v_pk_mul_f32 v[74:75], v[90:91], v[114:115] op_sel_hi:[1,0]
	v_cvt_pk_bf16_f32 v52, v44, v45
	v_pk_mul_f32 v[44:45], v[76:77], v[114:115] op_sel_hi:[1,0]
	v_lshl_add_u64 v[16:17], s[28:29], 0, v[16:17]
	v_cvt_pk_bf16_f32 v53, v44, v45
	global_load_dwordx2 v[44:45], v[112:113], off offset:32
	global_load_dwordx2 v[54:55], v[18:19], off offset:576
	global_load_dwordx2 v[58:59], v[70:71], off offset:256
	global_load_dwordx2 v[56:57], v[18:19], off offset:608
	global_load_dwordx2 v[62:63], v[18:19], off offset:768
	s_waitcnt vmcnt(12)
; __device__ __forceinline__ unsigned pk2(float lo, float hi) { f32x2 v = {lo, hi}; bf16v2_t b = __builtin_convertvector(v, bf16v2_t); return __builtin_bit_cast(unsigned, b); }
; __device__ __forceinline__ u32x2 pk4(f32x4 v) { u32x2 r; r.x = pk2(v.x, v.y); r.y = pk2(v.z, v.w); return r; }
; #define LAS __attribute__((address_space(3)))
; template <bool LDSRC>
; __device__ __forceinline__ void attn_core(const Params& p, const int lane, const char* kptr, const int kstride, const char* vptr, const int vstride,
;                                           const int kt0, const int has_prev, const int row_q, const int h_q, const int i_q) {
;     ...
; #pragma unroll
;   for (int pp = 0; pp < 5; ++pp) {
;     const int kA = 2 * pp, kB = (2 * pp + 1 < 9) ? 2 * pp + 1 : 2 * pp;
;     u32x4 pw;
;     pw.x = pk2(sa[kA][0] * inv, sa[kA][1] * inv); pw.y = pk2(sa[kA][2] * inv, sa[kA][3] * inv);
;     if (2 * pp + 1 < 9) { pw.z = pk2(sa[kB][0] * inv, sa[kB][1] * inv); pw.w = pk2(sa[kB][2] * inv, sa[kB][3] * inv); }
;     else { pw.z = 0u; pw.w = 0u; }
;     const bf16x8 pf = __builtin_bit_cast(bf16x8, pw);
;     if constexpr (LDSRC) {
;       int TA = kt0 + 2 * pp, TB = kt0 + ((2 * pp + 1 < 9) ? 2 * pp + 1 : 2 * pp);
;       if (!has_prev) { if (TA < 8) TA = 8; if (TB < 8) TB = 8; }
; #pragma unroll
;       for (int dt = 0; dt < 4; ++dt) {
;         const char* vp = vptr + (dt * 16 + pl) * vstride + q4 * 8;
;         const u32x2 va = *(const LAS u32x2*)(const LAS char*)(vp + TA * 32), vb = *(const LAS u32x2*)(const LAS char*)(vp + TB * 32);
;         oa[dt] = __builtin_amdgcn_mfma_f32_16x16x32_bf16(__builtin_bit_cast(bf16x8, u32x4{va.x, va.y, vb.x, vb.y}), pf, oa[dt], 0, 0, 0);
;       }
;     } else {
; #pragma unroll
;       for (int dt = 0; dt < 4; ++dt) oa[dt] = __builtin_amdgcn_mfma_f32_16x16x32_bf16(__builtin_bit_cast(bf16x8, vfr[pp][dt]), pf, oa[dt], 0, 0, 0);
;     }
;   }
;   bf16_t* O = (bf16_t*)(ws + OFF_O);
; #pragma unroll
;   for (int dt = 0; dt < 4; ++dt) *(u32x2*)(O + (size_t)row_q * 512 + h_q * 64 + dt * 16 + q4 * 4) = pk4(oa[dt]);
	v_mfma_f32_16x16x32_bf16 v[30:33], v[30:33], v[50:53], 0
	global_load_dwordx2 v[64:65], v[112:113], off offset:64
	global_load_dwordx2 v[66:67], v[112:113], off offset:96
	global_load_dwordx2 v[68:69], v[112:113], off offset:128
	global_load_dwordx2 v[72:73], v[110:111], off offset:1280
	v_lshl_add_u64 v[16:17], v[16:17], 0, v[8:9]
	v_mov_b32_e32 v3, v9
	s_waitcnt vmcnt(14)
	v_mfma_f32_16x16x32_bf16 v[34:37], v[34:37], v[50:53], 0
	v_lshl_add_u64 v[16:17], v[16:17], 0, v[2:3]
	s_waitcnt vmcnt(12)
	v_mfma_f32_16x16x32_bf16 v[38:41], v[38:41], v[50:53], 0
	s_waitcnt vmcnt(8)
	v_mfma_f32_16x16x32_bf16 v[42:45], v[42:45], v[50:53], 0
	v_mul_f32_e64 v50, v84, v114
	v_mul_f32_e64 v51, v85, v114
	v_pk_mul_f32 v[52:53], v[86:87], v[114:115] op_sel_hi:[1,0]
	v_cvt_pk_bf16_f32 v50, v50, v51
	v_cvt_pk_bf16_f32 v51, v52, v53
	v_pk_mul_f32 v[52:53], v[88:89], v[114:115] op_sel_hi:[1,0]
	s_nop 0
	v_cvt_pk_bf16_f32 v52, v52, v53
	v_cvt_pk_bf16_f32 v53, v74, v75
	s_nop 1
	v_mfma_f32_16x16x32_bf16 v[30:33], v[46:49], v[50:53], v[30:33]
	global_load_dwordx2 v[46:47], v[18:19], off offset:640
	global_load_dwordx2 v[48:49], v[18:19], off offset:672
	global_load_dwordx2 v[74:75], v[18:19], off offset:704
	s_waitcnt vmcnt(8)
	v_mfma_f32_16x16x32_bf16 v[34:37], v[54:57], v[50:53], v[34:37]
	global_load_dwordx2 v[54:55], v[110:111], off offset:1088
	global_load_dwordx2 v[56:57], v[110:111], off offset:1120
	global_load_dwordx2 v[84:85], v[110:111], off offset:1152
	global_load_dwordx2 v[86:87], v[110:111], off offset:1184
	s_waitcnt vmcnt(2)
	v_mfma_f32_16x16x32_bf16 v[38:41], v[54:57], v[50:53], v[38:41]
	global_load_dwordx2 v[54:55], v[70:71], off offset:128
	global_load_dwordx2 v[56:57], v[70:71], off offset:160
	global_load_dwordx2 v[88:89], v[70:71], off offset:192
	global_load_dwordx2 v[90:91], v[70:71], off offset:224
	s_nop 0
	global_load_dwordx2 v[70:71], v[112:113], off offset:160
	v_mfma_f32_16x16x32_bf16 v[42:45], v[64:67], v[50:53], v[42:45]
	v_mul_f32_e64 v50, v92, v114
	v_mul_f32_e64 v51, v93, v114
	v_pk_mul_f32 v[52:53], v[60:61], v[114:115] op_sel_hi:[1,0]
	v_cvt_pk_bf16_f32 v50, v50, v51
	v_cvt_pk_bf16_f32 v51, v52, v53
	v_pk_mul_f32 v[52:53], v[94:95], v[114:115] op_sel_hi:[1,0]
	v_pk_mul_f32 v[60:61], v[96:97], v[114:115] op_sel_hi:[1,0]
	v_cvt_pk_bf16_f32 v52, v52, v53
	v_cvt_pk_bf16_f32 v53, v60, v61
	v_mov_b32_e32 v60, v58
	v_mov_b32_e32 v61, v59
	s_waitcnt vmcnt(3)
	v_mfma_f32_16x16x32_bf16 v[30:33], v[54:57], v[50:53], v[30:33]
	v_mul_f32_e64 v56, v104, v114
	v_mul_f32_e64 v57, v105, v114
	v_mfma_f32_16x16x32_bf16 v[34:37], v[46:49], v[50:53], v[34:37]
	global_load_dwordx2 v[46:47], v[112:113], off offset:192
	global_load_dwordx2 v[48:49], v[112:113], off offset:224
	global_load_dwordx2 v[54:55], v[112:113], off offset:256
	global_load_dwordx2 v[76:77], v[18:19], off offset:736
	global_load_dwordx2 v[64:65], v[110:111], off offset:1216
	global_load_dwordx2 v[66:67], v[110:111], off offset:1248
	v_mfma_f32_16x16x32_bf16 v[38:41], v[84:87], v[50:53], v[38:41]
	v_mul_f32_e64 v18, v106, v114
	v_mul_f32_e64 v19, v107, v114
	s_waitcnt vmcnt(6)
	v_mfma_f32_16x16x32_bf16 v[42:45], v[68:71], v[50:53], v[42:45]
	v_mul_f32_e64 v50, v98, v114
	v_mul_f32_e64 v51, v99, v114
	v_pk_mul_f32 v[52:53], v[100:101], v[114:115] op_sel_hi:[1,0]
	v_cvt_pk_bf16_f32 v50, v50, v51
	v_cvt_pk_bf16_f32 v51, v52, v53
	v_pk_mul_f32 v[52:53], v[102:103], v[114:115] op_sel_hi:[1,0]
	s_nop 0
	v_cvt_pk_bf16_f32 v52, v52, v53
	v_cvt_pk_bf16_f32 v53, v56, v57
	s_waitcnt vmcnt(3)
	v_mov_b32_e32 v56, v54
	v_mfma_f32_16x16x32_bf16 v[30:33], v[88:91], v[50:53], v[30:33]
	v_mov_b32_e32 v57, v55
	s_waitcnt vmcnt(0)
	v_mfma_f32_16x16x32_bf16 v[38:41], v[64:67], v[50:53], v[38:41]
	v_mov_b32_e32 v64, v62
	v_mov_b32_e32 v65, v63
	v_mfma_f32_16x16x32_bf16 v[34:37], v[74:77], v[50:53], v[34:37]
	v_mov_b32_e32 v74, v72
	v_mov_b32_e32 v75, v73
	v_mfma_f32_16x16x32_bf16 v[42:45], v[46:49], v[50:53], v[42:45]
	v_cvt_pk_bf16_f32 v46, v18, v19
	v_pk_mul_f32 v[18:19], v[108:109], v[114:115] op_sel_hi:[1,0]
	v_mov_b32_e32 v48, v9
	v_cvt_pk_bf16_f32 v47, v18, v19
	v_mov_b32_e32 v49, v9
	s_nop 1
	v_mfma_f32_16x16x32_bf16 v[30:33], v[58:61], v[46:49], v[30:33]
	v_mfma_f32_16x16x32_bf16 v[34:37], v[62:65], v[46:49], v[34:37]
	v_mfma_f32_16x16x32_bf16 v[38:41], v[72:75], v[46:49], v[38:41]
	s_nop 5
	v_cvt_pk_bf16_f32 v18, v30, v31
	v_cvt_pk_bf16_f32 v19, v32, v33
	global_store_dwordx2 v[16:17], v[18:19], off
	v_mfma_f32_16x16x32_bf16 v[42:45], v[54:57], v[46:49], v[42:45]
	v_cvt_pk_bf16_f32 v18, v34, v35
	v_cvt_pk_bf16_f32 v19, v36, v37
	global_store_dwordx2 v[16:17], v[18:19], off offset:32
	v_cvt_pk_bf16_f32 v18, v38, v39
	v_cvt_pk_bf16_f32 v19, v40, v41
	global_store_dwordx2 v[16:17], v[18:19], off offset:64
	s_nop 1
	v_cvt_pk_bf16_f32 v18, v42, v43
	v_cvt_pk_bf16_f32 v19, v44, v45
	global_store_dwordx2 v[16:17], v[18:19], off offset:96
	s_branch .LBB0_544
